# GEMM prologues: K-tile 1's six LDS-DMA pieces issued right behind K-tile 0's eight (the vmcnt+barrier pair between the batches moved behind the second batch)
# speedup vs baseline: 1.0074x; 1.0018x over previous
.LBB0_146:
	s_mov_b64 s[26:27], 0x80
	s_and_b32 s0, s0, 3
	s_add_i32 m0, s82, 0x18000
	v_lshl_add_u64 v[6:7], v[6:7], 0, s[26:27]
	s_lshl_b32 s5, s1, 13
	s_lshl_b32 s86, s0, 5
	s_lshl_b32 s0, s0, 12
	global_load_lds_dwordx4 v[6:7], off
	v_lshl_add_u64 v[4:5], v[4:5], 0, s[26:27]
	s_add_i32 m0, s82, 0x1a000
	s_add_i32 s87, s82, 0x8000
	s_add_i32 s88, s82, 0xa000
	global_load_lds_dwordx4 v[4:5], off
	v_lshl_add_u64 v[0:1], v[0:1], 0, s[26:27]
	s_mov_b32 m0, s87
	s_add_u32 s6, s78, 0x40080
	global_load_lds_dwordx4 v[0:1], off
	v_lshl_add_u64 v[0:1], v[2:3], 0, s[26:27]
	s_mov_b32 m0, s88
	s_addc_u32 s7, s79, 0
	global_load_lds_dwordx4 v[0:1], off
	s_add_i32 m0, s82, 0x1c000
	v_lshl_add_u64 v[0:1], s[6:7], 0, v[146:147]
	global_load_lds_dwordx4 v[0:1], off
	v_lshl_add_u64 v[0:1], s[6:7], 0, v[150:151]
	s_add_i32 m0, s82, 0x1e000
	v_lshlrev_b32_e32 v4, 2, v8
	global_load_lds_dwordx4 v[0:1], off
	s_waitcnt vmcnt(8)
	s_barrier
	v_and_b32_e32 v0, 15, v8
	v_bfe_u32 v1, v8, 4, 2
	v_lshl_or_b32 v155, s1, 6, v0
	v_lshlrev_b32_e32 v2, 4, v1
	v_lshl_or_b32 v0, v0, 6, v2
	v_lshlrev_b32_e32 v2, 2, v155
	v_and_b32_e32 v3, 32, v2
	v_and_b32_e32 v4, 32, v4
	v_bitop3_b32 v3, v0, s5, v3 bitop3:0xde
	v_bitop3_b32 v180, v0, s0, v4 bitop3:0xde
	v_lshlrev_b32_e32 v0, 14, v9
	s_cmpk_lt_u32 s4, 0x100
	v_and_b32_e32 v0, 0xffff8000, v0
	v_lshlrev_b32_e32 v154, 3, v1
	s_cselect_b64 s[28:29], -1, 0
	s_bitcmp0_b32 s4, 6
	v_cmp_gt_u32_e64 s[0:1], 2, v1
	v_cmp_ne_u32_e64 s[4:5], 0, v1
	v_lshl_add_u32 v0, v10, 11, v0
	v_and_b32_e32 v1, 1, v9
	v_lshl_or_b32 v0, v1, 6, v0
	v_lshl_add_u32 v156, v11, 1, v0
	v_lshlrev_b32_e32 v0, 14, v12
	v_and_b32_e32 v0, 0xffff8000, v0
	s_waitcnt vmcnt(6)
	v_lshl_add_u32 v0, v13, 11, v0
	v_and_b32_e32 v1, 1, v12
	s_cselect_b64 s[30:31], -1, 0
	s_add_i32 s6, 0, 0x20000
	v_lshl_or_b32 v0, v1, 6, v0
	s_add_i32 s90, 0, 0x10000
	s_add_i32 s91, 0, 0x14000
	v_or_b32_e32 v182, s86, v154
	s_sub_i32 s89, 0x280, s86
	v_or_b32_e32 v184, 16, v155
	v_or_b32_e32 v185, 32, v155
	v_or_b32_e32 v186, 48, v155
	v_add_u32_e32 v187, 0x80, v155
	v_add_u32_e32 v188, 0x90, v155
	v_add_u32_e32 v189, 0xa0, v155
	v_add_u32_e32 v190, 0xb0, v155
	v_add_u32_e32 v191, s6, v2
	v_mov_b32_e32 v157, v153
	v_lshl_add_u32 v158, v14, 1, v0
	v_mov_b32_e32 v159, v153
	v_mov_b64_e32 v[160:161], 0x380
	v_mov_b64_e32 v[162:163], 0x37f
	v_add_u32_e32 v192, s90, v180
	v_add_u32_e32 v193, s91, v180
	v_add_u32_e32 v194, 0, v3
	s_movk_i32 s92, 0x600
	v_mbcnt_hi_u32_b32 v195, -1, v183
	s_mov_b32 s9, 0
	s_barrier
	s_branch .LBB0_149

.LBB0_607:
	s_mov_b64 s[10:11], 0x80
	s_and_b32 s38, s0, 3
	s_add_i32 m0, s34, 0x18000
	v_lshl_add_u64 v[6:7], v[6:7], 0, s[10:11]
	s_lshl_b32 s0, s1, 13
	s_lshl_b32 s5, s38, 12
	global_load_lds_dwordx4 v[6:7], off
	v_lshl_add_u64 v[4:5], v[4:5], 0, s[10:11]
	s_add_i32 m0, s34, 0x1a000
	s_add_i32 s39, s34, 0x8000
	s_add_i32 s40, s34, 0xa000
	global_load_lds_dwordx4 v[4:5], off
	v_lshl_add_u64 v[0:1], v[0:1], 0, s[10:11]
	s_mov_b32 m0, s39
	s_add_u32 s12, s26, 0x40080
	global_load_lds_dwordx4 v[0:1], off
	v_lshl_add_u64 v[0:1], v[2:3], 0, s[10:11]
	s_mov_b32 m0, s40
	s_addc_u32 s13, s27, 0
	global_load_lds_dwordx4 v[0:1], off
	s_add_i32 m0, s34, 0x1c000
	v_lshl_add_u64 v[0:1], s[12:13], 0, v[130:131]
	global_load_lds_dwordx4 v[0:1], off
	v_lshl_add_u64 v[0:1], s[12:13], 0, v[134:135]
	s_add_i32 m0, s34, 0x1e000
	s_cmpk_lt_u32 s4, 0x100
	global_load_lds_dwordx4 v[0:1], off
	s_waitcnt vmcnt(8)
	s_barrier
	v_bfe_u32 v0, v8, 4, 2
	v_and_b32_e32 v1, 15, v8
	v_lshlrev_b32_e32 v3, 4, v0
	v_lshl_or_b32 v148, s1, 6, v1
	v_lshl_or_b32 v1, v1, 6, v3
	v_lshlrev_b32_e32 v3, 2, v8
	v_and_b32_e32 v3, 32, v3
	v_lshlrev_b32_e32 v2, 3, v0
	v_bitop3_b32 v4, v1, s0, v3 bitop3:0xde
	v_cmp_eq_u32_e64 s[0:1], 0, v0
	v_lshlrev_b32_e32 v0, 14, v9
	v_and_b32_e32 v0, 0xffff8000, v0
	v_bitop3_b32 v149, v1, s5, v3 bitop3:0xde
	v_lshl_add_u32 v0, v10, 11, v0
	v_and_b32_e32 v1, 1, v9
	v_lshl_or_b32 v0, v1, 6, v0
	v_lshl_add_u32 v136, v11, 1, v0
	v_lshlrev_b32_e32 v0, 14, v12
	v_and_b32_e32 v0, 0xffff8000, v0
	s_waitcnt vmcnt(6)
	v_lshl_add_u32 v0, v13, 11, v0
	v_and_b32_e32 v1, 1, v12
	s_cselect_b64 s[12:13], -1, 0
	v_lshl_or_b32 v0, v1, 6, v0
	s_add_i32 s41, 0, 0x10000
	s_add_i32 s42, 0, 0x14000
	v_lshl_or_b32 v150, s38, 5, v2
	v_mov_b32_e32 v137, v131
	v_lshl_add_u32 v138, v14, 1, v0
	v_mov_b32_e32 v139, v131
	v_mov_b64_e32 v[140:141], 0x200
	v_mov_b64_e32 v[142:143], 0x1ff
	v_add_u32_e32 v151, s41, v149
	v_add_u32_e32 v152, s42, v149
	v_add_u32_e32 v153, 0, v4
	v_mbcnt_hi_u32_b32 v154, -1, v183
	s_mov_b32 s43, 0
	s_barrier
	s_branch .LBB0_610

.LBB0_699:
	s_lshl_b32 s6, s6, 5
	s_and_b32 s12, s6, 0x60
	s_mov_b64 s[6:7], 0x80
	s_add_i32 m0, s19, 0x18000
	v_lshl_add_u64 v[6:7], v[6:7], 0, s[6:7]
	s_lshl_b32 s9, s8, 13
	s_lshl_b32 s13, s12, 7
	global_load_lds_dwordx4 v[6:7], off
	v_lshl_add_u64 v[4:5], v[4:5], 0, s[6:7]
	s_add_i32 m0, s19, 0x1a000
	s_add_i32 s34, s19, 0x8000
	s_add_i32 s35, s19, 0xa000
	global_load_lds_dwordx4 v[4:5], off
	v_lshl_add_u64 v[0:1], v[0:1], 0, s[6:7]
	s_mov_b32 m0, s34
	s_add_u32 s10, s22, 0x40080
	global_load_lds_dwordx4 v[0:1], off
	v_lshl_add_u64 v[0:1], v[2:3], 0, s[6:7]
	s_mov_b32 m0, s35
	s_addc_u32 s11, s23, 0
	global_load_lds_dwordx4 v[0:1], off
	s_add_i32 m0, s19, 0x1c000
	v_lshl_add_u64 v[0:1], s[10:11], 0, v[132:133]
	global_load_lds_dwordx4 v[0:1], off
	v_lshl_add_u64 v[0:1], s[10:11], 0, v[128:129]
	s_add_i32 m0, s19, 0x1e000
	v_lshlrev_b32_e32 v4, 2, v9
	global_load_lds_dwordx4 v[0:1], off
	s_waitcnt vmcnt(8)
	s_barrier
	v_lshrrev_b32_e32 v1, 1, v9
	v_and_b32_e32 v0, 15, v9
	v_and_b32_e32 v1, 24, v1
	v_lshl_or_b32 v144, s8, 6, v0
	v_lshlrev_b32_e32 v2, 1, v1
	v_lshl_or_b32 v0, v0, 6, v2
	v_lshlrev_b32_e32 v2, 2, v144
	v_and_b32_e32 v3, 32, v2
	v_and_b32_e32 v4, 32, v4
	v_bitop3_b32 v3, v0, s9, v3 bitop3:0xde
	v_bitop3_b32 v145, v0, s13, v4 bitop3:0xde
	v_lshlrev_b32_e32 v0, 14, v13
	v_and_b32_e32 v0, 0xffff8000, v0
	v_or_b32_e32 v149, s12, v1
	v_lshl_add_u32 v0, v12, 11, v0
	v_and_b32_e32 v1, 1, v13
	v_lshl_or_b32 v0, v1, 6, v0
	v_lshl_add_u32 v136, v14, 1, v0
	v_lshlrev_b32_e32 v0, 14, v8
	v_and_b32_e32 v0, 0xffff8000, v0
	s_waitcnt vmcnt(6)
	s_cmpk_lt_u32 s1, 0x100
	v_lshl_add_u32 v0, v10, 11, v0
	v_and_b32_e32 v1, 1, v8
	s_sext_i32_i16 s41, s0
	s_cselect_b64 s[8:9], -1, 0
	s_add_i32 s0, 0, 0x20000
	v_lshl_or_b32 v0, v1, 6, v0
	s_add_i32 s36, 0, 0x10000
	s_add_i32 s37, 0, 0x14000
	v_or_b32_e32 v146, 16, v144
	v_or_b32_e32 v147, 32, v144
	v_or_b32_e32 v148, 48, v144
	v_add_u32_e32 v150, s0, v2
	v_mov_b32_e32 v137, v133
	v_lshl_add_u32 v138, v11, 1, v0
	v_mov_b32_e32 v139, v133
	v_mov_b64_e32 v[140:141], 0xb00
	v_mov_b64_e32 v[142:143], 0xaff
	v_add_u32_e32 v151, s36, v145
	v_add_u32_e32 v152, s37, v145
	v_add_u32_e32 v153, 0, v3
	s_movk_i32 s38, 0x1600
	s_barrier
	s_branch .LBB0_702

.LBB0_773:
	s_mov_b64 s[12:13], 0x80
	s_and_b32 s34, s0, 3
	s_add_i32 m0, s29, 0x18000
	v_lshl_add_u64 v[6:7], v[6:7], 0, s[12:13]
	s_lshl_b32 s0, s1, 13
	s_lshl_b32 s14, s34, 12
	global_load_lds_dwordx4 v[6:7], off
	v_lshl_add_u64 v[4:5], v[4:5], 0, s[12:13]
	s_add_i32 m0, s29, 0x1a000
	s_add_i32 s35, s29, 0x8000
	s_add_i32 s36, s29, 0xa000
	global_load_lds_dwordx4 v[4:5], off
	v_lshl_add_u64 v[0:1], v[0:1], 0, s[12:13]
	s_mov_b32 m0, s35
	s_add_u32 s6, s20, 0xb0080
	global_load_lds_dwordx4 v[0:1], off
	v_lshl_add_u64 v[0:1], v[2:3], 0, s[12:13]
	s_mov_b32 m0, s36
	s_addc_u32 s7, s21, 0
	global_load_lds_dwordx4 v[0:1], off
	s_add_i32 m0, s29, 0x1c000
	v_lshl_add_u64 v[0:1], s[6:7], 0, v[130:131]
	global_load_lds_dwordx4 v[0:1], off
	v_lshl_add_u64 v[0:1], s[6:7], 0, v[134:135]
	s_add_i32 m0, s29, 0x1e000
	s_cmpk_lt_u32 s4, 0x100
	global_load_lds_dwordx4 v[0:1], off
	s_waitcnt vmcnt(8)
	s_barrier
	v_bfe_u32 v0, v8, 4, 2
	v_and_b32_e32 v1, 15, v8
	v_lshlrev_b32_e32 v3, 4, v0
	v_lshl_or_b32 v148, s1, 6, v1
	v_lshl_or_b32 v1, v1, 6, v3
	v_lshlrev_b32_e32 v3, 2, v8
	v_and_b32_e32 v3, 32, v3
	v_lshlrev_b32_e32 v2, 3, v0
	v_bitop3_b32 v4, v1, s0, v3 bitop3:0xde
	v_bitop3_b32 v149, v1, s14, v3 bitop3:0xde
	v_cmp_eq_u32_e64 s[0:1], 0, v0
	v_lshrrev_b32_e32 v1, 1, v9
	v_mul_lo_u32 v0, v11, s5
	s_mov_b32 s4, 0xb000
	v_mad_u64_u32 v[0:1], s[16:17], v1, s4, v[0:1]
	v_or_b32_e32 v0, v0, v10
	s_mov_b64 s[6:7], 0xb0080
	v_add_lshl_u32 v0, v0, v12, 1
	v_mov_b32_e32 v1, v131
	v_lshl_add_u64 v[136:137], v[0:1], 0, s[6:7]
	v_lshrrev_b32_e32 v1, 1, v13
	v_mul_lo_u32 v0, v14, s5
	v_mad_u64_u32 v[0:1], s[4:5], v1, s4, v[0:1]
	s_waitcnt vmcnt(6)
	v_or_b32_e32 v0, v0, v15
	s_cselect_b64 s[14:15], -1, 0
	v_add_lshl_u32 v0, v0, v16, 1
	v_mov_b32_e32 v1, v131
	s_add_i32 s37, 0, 0x10000
	s_add_i32 s38, 0, 0x14000
	v_lshl_or_b32 v150, s34, 5, v2
	v_lshl_add_u64 v[138:139], v[0:1], 0, s[6:7]
	v_mov_b64_e32 v[140:141], 0x200
	v_mov_b64_e32 v[142:143], 0x1ff
	v_add_u32_e32 v151, s37, v149
	v_add_u32_e32 v152, s38, v149
	v_add_u32_e32 v153, 0, v4
	v_mbcnt_hi_u32_b32 v154, -1, v183
	s_mov_b32 s39, 0
	s_barrier
	s_branch .LBB0_776

.LBB0_871:
	s_mov_b64 s[14:15], 0x80
	s_and_b32 s0, s0, 3
	s_add_i32 m0, s38, 0x18000
	v_lshl_add_u64 v[6:7], v[6:7], 0, s[14:15]
	s_lshl_b32 s5, s1, 13
	s_lshl_b32 s11, s0, 12
	global_load_lds_dwordx4 v[6:7], off
	v_lshl_add_u64 v[4:5], v[4:5], 0, s[14:15]
	s_add_i32 m0, s38, 0x1a000
	s_add_i32 s42, s38, 0x8000
	s_add_i32 s43, s38, 0xa000
	global_load_lds_dwordx4 v[4:5], off
	v_lshl_add_u64 v[0:1], v[0:1], 0, s[14:15]
	s_mov_b32 m0, s42
	s_add_u32 s6, s30, 0x40080
	global_load_lds_dwordx4 v[0:1], off
	v_lshl_add_u64 v[0:1], v[2:3], 0, s[14:15]
	s_mov_b32 m0, s43
	s_addc_u32 s7, s31, 0
	global_load_lds_dwordx4 v[0:1], off
	s_add_i32 m0, s38, 0x1c000
	v_lshl_add_u64 v[0:1], s[6:7], 0, v[130:131]
	global_load_lds_dwordx4 v[0:1], off
	v_lshl_add_u64 v[0:1], s[6:7], 0, v[134:135]
	s_add_i32 m0, s38, 0x1e000
	v_lshlrev_b32_e32 v5, 2, v8
	global_load_lds_dwordx4 v[0:1], off
	s_waitcnt vmcnt(8)
	s_barrier
	v_and_b32_e32 v0, 15, v8
	v_bfe_u32 v1, v8, 4, 2
	v_lshl_or_b32 v162, s1, 6, v0
	v_lshlrev_b32_e32 v3, 4, v1
	v_lshl_or_b32 v0, v0, 6, v3
	v_lshlrev_b32_e32 v3, 2, v162
	v_and_b32_e32 v4, 32, v3
	v_and_b32_e32 v5, 32, v5
	v_bitop3_b32 v4, v0, s5, v4 bitop3:0xde
	v_bitop3_b32 v163, v0, s11, v5 bitop3:0xde
	v_lshlrev_b32_e32 v0, 14, v9
	v_lshlrev_b32_e32 v2, 3, v1
	s_cmpk_lt_u32 s4, 0x100
	v_and_b32_e32 v0, 0xffff8000, v0
	v_lshl_or_b32 v164, s0, 5, v2
	s_cselect_b64 s[16:17], -1, 0
	s_bitcmp0_b32 s4, 6
	v_cmp_gt_u32_e64 s[0:1], 2, v1
	v_cmp_ne_u32_e64 s[4:5], 0, v1
	v_lshl_add_u32 v0, v10, 11, v0
	v_and_b32_e32 v1, 1, v9
	v_lshl_or_b32 v0, v1, 6, v0
	v_lshl_add_u32 v136, v11, 1, v0
	v_lshlrev_b32_e32 v0, 14, v12
	v_and_b32_e32 v0, 0xffff8000, v0
	s_waitcnt vmcnt(6)
	v_lshl_add_u32 v0, v13, 11, v0
	v_and_b32_e32 v1, 1, v12
	s_cselect_b64 s[18:19], -1, 0
	s_add_i32 s6, 0, 0x20000
	v_lshl_or_b32 v0, v1, 6, v0
	s_add_i32 s47, 0, 0x10000
	s_add_i32 s50, 0, 0x14000
	v_or_b32_e32 v165, 16, v162
	v_or_b32_e32 v166, 32, v162
	v_or_b32_e32 v167, 48, v162
	v_add_u32_e32 v168, 0x80, v162
	v_add_u32_e32 v169, 0x90, v162
	v_add_u32_e32 v170, 0xa0, v162
	v_add_u32_e32 v171, 0xb0, v162
	v_add_u32_e32 v172, s6, v3
	v_mov_b32_e32 v137, v131
	v_lshl_add_u32 v138, v14, 1, v0
	v_mov_b32_e32 v139, v131
	v_mov_b64_e32 v[140:141], 0x500
	v_mov_b64_e32 v[142:143], 0x4ff
	s_movk_i32 s46, 0xa1
	v_add_u32_e32 v173, s47, v163
	v_add_u32_e32 v174, s50, v163
	v_add_u32_e32 v175, 0, v4
	s_movk_i32 s51, 0x1400
	v_mbcnt_hi_u32_b32 v176, -1, v183
	s_barrier
	s_branch .LBB0_874

.LBB0_1373:
	s_lshl_b32 s6, s6, 5
	s_and_b32 s12, s6, 0x60
	s_mov_b64 s[6:7], 0x80
	s_add_i32 m0, s19, 0x18000
	v_lshl_add_u64 v[6:7], v[6:7], 0, s[6:7]
	s_lshl_b32 s9, s8, 13
	s_lshl_b32 s13, s12, 7
	global_load_lds_dwordx4 v[6:7], off
	v_lshl_add_u64 v[4:5], v[4:5], 0, s[6:7]
	s_add_i32 m0, s19, 0x1a000
	s_add_i32 s34, s19, 0x8000
	s_add_i32 s35, s19, 0xa000
	global_load_lds_dwordx4 v[4:5], off
	v_lshl_add_u64 v[0:1], v[0:1], 0, s[6:7]
	s_mov_b32 m0, s34
	s_add_u32 s10, s22, 0x40080
	global_load_lds_dwordx4 v[0:1], off
	v_lshl_add_u64 v[0:1], v[2:3], 0, s[6:7]
	s_mov_b32 m0, s35
	s_addc_u32 s11, s23, 0
	global_load_lds_dwordx4 v[0:1], off
	s_add_i32 m0, s19, 0x1c000
	v_lshl_add_u64 v[0:1], s[10:11], 0, v[132:133]
	global_load_lds_dwordx4 v[0:1], off
	v_lshl_add_u64 v[0:1], s[10:11], 0, v[128:129]
	s_add_i32 m0, s19, 0x1e000
	v_lshlrev_b32_e32 v4, 2, v9
	global_load_lds_dwordx4 v[0:1], off
	s_waitcnt vmcnt(8)
	s_barrier
	v_lshrrev_b32_e32 v1, 1, v9
	v_and_b32_e32 v0, 15, v9
	v_and_b32_e32 v1, 24, v1
	s_waitcnt vmcnt(0)
	v_lshl_or_b32 v144, s8, 6, v0
	v_lshlrev_b32_e32 v2, 1, v1
	v_lshl_or_b32 v0, v0, 6, v2
	v_lshlrev_b32_e32 v2, 2, v144
	v_and_b32_e32 v3, 32, v2
	v_and_b32_e32 v4, 32, v4
	v_bitop3_b32 v3, v0, s9, v3 bitop3:0xde
	v_bitop3_b32 v145, v0, s13, v4 bitop3:0xde
	v_lshlrev_b32_e32 v0, 14, v13
	v_and_b32_e32 v0, 0xffff8000, v0
	v_or_b32_e32 v149, s12, v1
	v_lshl_add_u32 v0, v12, 11, v0
	v_and_b32_e32 v1, 1, v13
	v_lshl_or_b32 v0, v1, 6, v0
	v_lshl_add_u32 v136, v14, 1, v0
	v_lshlrev_b32_e32 v0, 14, v8
	v_and_b32_e32 v0, 0xffff8000, v0
	s_waitcnt vmcnt(6)
	s_cmpk_lt_u32 s1, 0x100
	v_lshl_add_u32 v0, v10, 11, v0
	v_and_b32_e32 v1, 1, v8
	s_sext_i32_i16 s41, s0
	s_cselect_b64 s[8:9], -1, 0
	s_add_i32 s0, 0, 0x20000
	v_lshl_or_b32 v0, v1, 6, v0
	s_add_i32 s36, 0, 0x10000
	s_add_i32 s37, 0, 0x14000
	v_or_b32_e32 v146, 16, v144
	v_or_b32_e32 v147, 32, v144
	v_or_b32_e32 v148, 48, v144
	v_add_u32_e32 v150, s0, v2
	v_mov_b32_e32 v137, v133
	v_lshl_add_u32 v138, v11, 1, v0
	v_mov_b32_e32 v139, v133
	v_mov_b64_e32 v[140:141], 0xb00
	v_mov_b64_e32 v[142:143], 0xaff
	v_add_u32_e32 v151, s36, v145
	v_add_u32_e32 v152, s37, v145
	v_add_u32_e32 v153, 0, v3
	s_movk_i32 s38, 0x1600
	s_barrier
	s_branch .LBB0_1376
